# diff attn: PV stages re-spaced (VALU spread between MFMAs), barrier at last-stage head, static prio waves 4-7, in-proj epilogue rstd loads hoisted
# speedup vs baseline: 1.0309x; 1.0082x over previous
;     __device__ __forceinline__ void operator()(const pg8::f32x4 (&acc)[2][2][4][2], const pg8::Unit& u, int wr, int wc, int fr, int fq) const {
;     ...
;         const int row0 = u.pm * 256 + wr * 64 + fr, col0 = wc * 32 + 8 * fq;
;         const bool dorope = rope && ((wc & 1) == 0);
;         const float sgn = (fq == 0) ? -1.f : 1.f;
; #pragma unroll
;         for (int ai = 0; ai < 2; ++ai)
; #pragma unroll
;             for (int m = 0; m < 4; ++m) {
;                 const int row = row0 + ai * 128 + m * 16;
;                 const int tok = row & (SEQ - 1);
;                 bf16_t* rowp = base + (size_t)((row >> 13) * LP + PADF + NMETA + tok) * ldc + col0;
;                 const float scr = sc * rstd[row];
;                 f32x4 c0 = {1.f, 1.f, 1.f, 1.f}, c1 = c0, s0 = {0.f, 0.f, 0.f, 0.f}, s1 = s0;
;                 if (dorope) {
;                     const int pos = NMETA + tok;
;                     if (fq < 2) { c0 = *(const f32x4*)(ropec + pos * 8); c1 = *(const f32x4*)(ropec + pos * 8 + 4); s0 = *(const f32x4*)(ropes + pos * 8); s1 = *(const f32x4*)(ropes + pos * 8 + 4); }
.LBB0_335:
	v_lshl_add_u64 v[134:135], v[134:135], 2, s[72:73]
	global_load_dword v165, v[134:135], off
	global_load_dword v224, v[134:135], off offset:64
	global_load_dword v225, v[134:135], off offset:128
	global_load_dword v226, v[134:135], off offset:192
	global_load_dword v227, v[134:135], off offset:512
	global_load_dword v228, v[134:135], off offset:576
	global_load_dword v229, v[134:135], off offset:640
	global_load_dword v230, v[134:135], off offset:704
	s_and_b64 s[24:25], s[14:15], s[24:25]
	v_mov_b32_e32 v146, 0
	v_mov_b32_e32 v138, 1.0
	s_and_b64 s[30:31], s[24:25], s[42:43]
	v_and_b32_e32 v167, 0x1fcf, v166
	v_mov_b32_e32 v139, v138
	v_mov_b32_e32 v140, v138
	v_mov_b32_e32 v141, v138
	v_mov_b32_e32 v134, v138
	v_mov_b32_e32 v135, v138
	v_mov_b32_e32 v136, v138
	s_waitcnt lgkmcnt(0)
	v_mov_b32_e32 v137, v138
	v_mov_b32_e32 v147, v146
	v_mov_b32_e32 v148, v146
	v_mov_b32_e32 v149, v146
	v_mov_b32_e32 v142, v146
	v_mov_b32_e32 v143, v146
	v_mov_b32_e32 v144, v146
	v_mov_b32_e32 v145, v146
	s_and_saveexec_b64 s[28:29], s[30:31]
	s_cbranch_execz .LBB0_337
	v_readlane_b32 s22, v253, 20
	v_lshl_or_b32 v142, v167, 5, v220
	v_readlane_b32 s23, v253, 21
	s_nop 4
	global_load_dwordx4 v[138:141], v142, s[22:23]
	global_load_dwordx4 v[134:137], v142, s[22:23] offset:16
	v_readlane_b32 s22, v253, 22
	v_readlane_b32 s23, v253, 23
	s_nop 4
	global_load_dwordx4 v[146:149], v142, s[22:23]
	s_nop 0
	global_load_dwordx4 v[142:145], v142, s[22:23] offset:16

;     __device__ __forceinline__ void operator()(const pg8::f32x4 (&acc)[2][2][4][2], const pg8::Unit& u, int wr, int wc, int fr, int fq) const {
;     ...
;                 const int row = row0 + ai * 128 + m * 16;
;                 const int tok = row & (SEQ - 1);
;                 bf16_t* rowp = base + (size_t)((row >> 13) * LP + PADF + NMETA + tok) * ldc + col0;
;                 const float scr = sc * rstd[row];
;                 f32x4 c0 = {1.f, 1.f, 1.f, 1.f}, c1 = c0, s0 = {0.f, 0.f, 0.f, 0.f}, s1 = s0;
;                 if (dorope) {
;                     const int pos = NMETA + tok;
;                     if (fq < 2) { c0 = *(const f32x4*)(ropec + pos * 8); c1 = *(const f32x4*)(ropec + pos * 8 + 4); s0 = *(const f32x4*)(ropes + pos * 8); s1 = *(const f32x4*)(ropes + pos * 8 + 4); }
;                 }
; #pragma unroll
;                 for (int bj = 0; bj < 2; ++bj) {
;                     f32x4 v0 = acc[ai][bj][m][0] * scr, v1 = acc[ai][bj][m][1] * scr;
;                     if (dorope) {
;                         f32x4 p0, p1;
; #pragma unroll
;                         for (int e = 0; e < 4; ++e) { p0[e] = __shfl_xor(v0[e], 16); p1[e] = __shfl_xor(v1[e], 16); }
;                         v0 = v0 * c0 + (p0 * s0) * sgn; v1 = v1 * c1 + (p1 * s1) * sgn;
.LBB0_345:
	v_cvt_pk_bf16_f32 v122, v122, v123
	v_cvt_pk_bf16_f32 v123, v124, v125
	v_cvt_pk_bf16_f32 v124, v118, v119
	v_or_b32_e32 v118, 16, v166
	v_cvt_pk_bf16_f32 v125, v120, v121
	v_ashrrev_i32_e32 v119, 31, v118
	global_store_dwordx4 v[126:127], v[122:125], off offset:256
	v_lshl_add_u64 v[118:119], v[118:119], 2, s[72:73]
	v_mov_b32_e32 v134, v224
	s_movk_i32 s0, 0x1fdf
	v_bitop3_b32 v138, v166, s0, 16 bitop3:0xc8
	v_mov_b32_e32 v130, 0
	v_mov_b32_e32 v122, 1.0
	v_mov_b32_e32 v123, 1.0
	v_mov_b32_e32 v124, 1.0
	v_mov_b32_e32 v125, 1.0
	v_mov_b32_e32 v118, 1.0
	v_mov_b32_e32 v119, 1.0
	v_mov_b32_e32 v120, 1.0
	v_mov_b32_e32 v121, 1.0
	v_mov_b32_e32 v131, 0
	v_mov_b32_e32 v132, 0
	v_mov_b32_e32 v133, 0
	v_mov_b32_e32 v126, 0
	v_mov_b32_e32 v127, 0
	v_mov_b32_e32 v128, 0
	v_mov_b32_e32 v129, 0
	s_and_saveexec_b64 s[20:21], s[30:31]
	s_cbranch_execz .LBB0_347
	v_readlane_b32 s0, v253, 20
	v_lshl_add_u32 v126, v138, 5, v220
	v_readlane_b32 s1, v253, 21
	s_nop 4
	global_load_dwordx4 v[122:125], v126, s[0:1]
	global_load_dwordx4 v[118:121], v126, s[0:1] offset:16
	v_readlane_b32 s0, v253, 22
	v_readlane_b32 s1, v253, 23
	s_nop 4
	global_load_dwordx4 v[130:133], v126, s[0:1]
	s_nop 0
	global_load_dwordx4 v[126:129], v126, s[0:1] offset:16
	s_waitcnt vmcnt(0)
.LBB0_347:
	s_or_b64 exec, exec, s[20:21]
	v_mul_f32_e32 v134, s19, v134
	v_pk_mul_f32 v[116:117], v[116:117], v[134:135] op_sel_hi:[1,0]
	v_pk_mul_f32 v[114:115], v[114:115], v[134:135] op_sel_hi:[1,0]
	v_pk_mul_f32 v[112:113], v[112:113], v[134:135] op_sel_hi:[1,0]
	s_and_b64 vcc, exec, s[46:47]
	v_pk_mul_f32 v[136:137], v[110:111], v[134:135] op_sel_hi:[1,0]
	s_cbranch_vccnz .LBB0_349
	v_and_b32_e32 v111, 64, v218
	v_xor_b32_e32 v110, 16, v218
	v_add_u32_e32 v111, 64, v111
	v_cmp_lt_i32_e32 vcc, v110, v111
	s_nop 1
	v_cndmask_b32_e32 v110, v218, v110, vcc
	v_lshlrev_b32_e32 v135, 2, v110
	ds_bpermute_b32 v110, v135, v114
	ds_bpermute_b32 v111, v135, v115
	ds_bpermute_b32 v140, v135, v136
	ds_bpermute_b32 v142, v135, v116
	ds_bpermute_b32 v143, v135, v117
	ds_bpermute_b32 v141, v135, v137
	ds_bpermute_b32 v144, v135, v112
	ds_bpermute_b32 v145, v135, v113
	s_waitcnt lgkmcnt(6)
	v_pk_mul_f32 v[110:111], v[130:131], v[110:111]
	s_waitcnt lgkmcnt(3)
	v_pk_mul_f32 v[142:143], v[132:133], v[142:143]
	v_pk_mul_f32 v[110:111], v[156:157], v[110:111]
	s_waitcnt lgkmcnt(2)
	v_pk_mul_f32 v[140:141], v[126:127], v[140:141]
	v_pk_fma_f32 v[114:115], v[114:115], v[122:123], v[110:111]
	s_waitcnt lgkmcnt(0)
	v_pk_mul_f32 v[110:111], v[128:129], v[144:145]
	v_pk_mul_f32 v[142:143], v[158:159], v[142:143]
	v_pk_mul_f32 v[140:141], v[156:157], v[140:141]
	v_pk_mul_f32 v[110:111], v[158:159], v[110:111]
	v_pk_fma_f32 v[116:117], v[116:117], v[124:125], v[142:143]
	v_pk_fma_f32 v[112:113], v[112:113], v[120:121], v[110:111]
	v_pk_fma_f32 v[136:137], v[136:137], v[118:119], v[140:141]

;     __device__ __forceinline__ void operator()(const pg8::f32x4 (&acc)[2][2][4][2], const pg8::Unit& u, int wr, int wc, int fr, int fq) const {
;     ...
;                 const int row = row0 + ai * 128 + m * 16;
;                 const int tok = row & (SEQ - 1);
;                 bf16_t* rowp = base + (size_t)((row >> 13) * LP + PADF + NMETA + tok) * ldc + col0;
;                 const float scr = sc * rstd[row];
;                 f32x4 c0 = {1.f, 1.f, 1.f, 1.f}, c1 = c0, s0 = {0.f, 0.f, 0.f, 0.f}, s1 = s0;
;                 if (dorope) {
;                     const int pos = NMETA + tok;
;                     if (fq < 2) { c0 = *(const f32x4*)(ropec + pos * 8); c1 = *(const f32x4*)(ropec + pos * 8 + 4); s0 = *(const f32x4*)(ropes + pos * 8); s1 = *(const f32x4*)(ropes + pos * 8 + 4); }
;                 }
; #pragma unroll
;                 for (int bj = 0; bj < 2; ++bj) {
;                     f32x4 v0 = acc[ai][bj][m][0] * scr, v1 = acc[ai][bj][m][1] * scr;
;                     if (dorope) {
;                         f32x4 p0, p1;
; #pragma unroll
;                         for (int e = 0; e < 4; ++e) { p0[e] = __shfl_xor(v0[e], 16); p1[e] = __shfl_xor(v1[e], 16); }
;                         v0 = v0 * c0 + (p0 * s0) * sgn; v1 = v1 * c1 + (p1 * s1) * sgn;
.LBB0_355:
	v_cvt_pk_bf16_f32 v106, v106, v107
	v_cvt_pk_bf16_f32 v107, v108, v109
	v_cvt_pk_bf16_f32 v108, v102, v103
	v_or_b32_e32 v102, 32, v166
	v_cvt_pk_bf16_f32 v109, v104, v105
	v_ashrrev_i32_e32 v103, 31, v102
	global_store_dwordx4 v[110:111], v[106:109], off offset:256
	v_lshl_add_u64 v[102:103], v[102:103], 2, s[72:73]
	v_mov_b32_e32 v118, v225
	s_movk_i32 s0, 0x1fef
	v_bitop3_b32 v122, v166, s0, 32 bitop3:0xc8
	v_mov_b32_e32 v114, 0
	v_mov_b32_e32 v106, 1.0
	v_mov_b32_e32 v107, 1.0
	v_mov_b32_e32 v108, 1.0
	v_mov_b32_e32 v109, 1.0
	v_mov_b32_e32 v102, 1.0
	v_mov_b32_e32 v103, 1.0
	v_mov_b32_e32 v104, 1.0
	v_mov_b32_e32 v105, 1.0
	v_mov_b32_e32 v115, 0
	v_mov_b32_e32 v116, 0
	v_mov_b32_e32 v117, 0
	v_mov_b32_e32 v110, 0
	v_mov_b32_e32 v111, 0
	v_mov_b32_e32 v112, 0
	v_mov_b32_e32 v113, 0
	s_and_saveexec_b64 s[20:21], s[30:31]
	s_cbranch_execz .LBB0_357
	v_readlane_b32 s0, v253, 20
	v_lshl_or_b32 v110, v122, 5, v220
	v_readlane_b32 s1, v253, 21
	s_nop 4
	global_load_dwordx4 v[106:109], v110, s[0:1]
	global_load_dwordx4 v[102:105], v110, s[0:1] offset:16
	v_readlane_b32 s0, v253, 22
	v_readlane_b32 s1, v253, 23
	s_nop 4
	global_load_dwordx4 v[114:117], v110, s[0:1]
	s_nop 0
	global_load_dwordx4 v[110:113], v110, s[0:1] offset:16
	s_waitcnt vmcnt(0)
.LBB0_357:
	s_or_b64 exec, exec, s[20:21]
	v_mul_f32_e32 v118, s19, v118
	v_pk_mul_f32 v[100:101], v[100:101], v[118:119] op_sel_hi:[1,0]
	v_pk_mul_f32 v[98:99], v[98:99], v[118:119] op_sel_hi:[1,0]
	v_pk_mul_f32 v[96:97], v[96:97], v[118:119] op_sel_hi:[1,0]
	s_and_b64 vcc, exec, s[46:47]
	v_pk_mul_f32 v[120:121], v[94:95], v[118:119] op_sel_hi:[1,0]
	s_cbranch_vccnz .LBB0_359
	v_and_b32_e32 v95, 64, v218
	v_xor_b32_e32 v94, 16, v218
	v_add_u32_e32 v95, 64, v95
	v_cmp_lt_i32_e32 vcc, v94, v95
	s_nop 1
	v_cndmask_b32_e32 v94, v218, v94, vcc
	v_lshlrev_b32_e32 v119, 2, v94
	ds_bpermute_b32 v94, v119, v98
	ds_bpermute_b32 v95, v119, v99
	ds_bpermute_b32 v124, v119, v120
	ds_bpermute_b32 v126, v119, v100
	ds_bpermute_b32 v127, v119, v101
	ds_bpermute_b32 v125, v119, v121
	ds_bpermute_b32 v128, v119, v96
	ds_bpermute_b32 v129, v119, v97
	s_waitcnt lgkmcnt(6)
	v_pk_mul_f32 v[94:95], v[114:115], v[94:95]
	s_waitcnt lgkmcnt(3)
	v_pk_mul_f32 v[126:127], v[116:117], v[126:127]
	v_pk_mul_f32 v[94:95], v[156:157], v[94:95]
	s_waitcnt lgkmcnt(2)
	v_pk_mul_f32 v[124:125], v[110:111], v[124:125]
	v_pk_fma_f32 v[98:99], v[98:99], v[106:107], v[94:95]
	s_waitcnt lgkmcnt(0)
	v_pk_mul_f32 v[94:95], v[112:113], v[128:129]
	v_pk_mul_f32 v[126:127], v[158:159], v[126:127]
	v_pk_mul_f32 v[124:125], v[156:157], v[124:125]
	v_pk_mul_f32 v[94:95], v[158:159], v[94:95]
	v_pk_fma_f32 v[100:101], v[100:101], v[108:109], v[126:127]
	v_pk_fma_f32 v[96:97], v[96:97], v[104:105], v[94:95]
	v_pk_fma_f32 v[120:121], v[120:121], v[102:103], v[124:125]

;     __device__ __forceinline__ void operator()(const pg8::f32x4 (&acc)[2][2][4][2], const pg8::Unit& u, int wr, int wc, int fr, int fq) const {
;     ...
;                 const int row = row0 + ai * 128 + m * 16;
;                 const int tok = row & (SEQ - 1);
;                 bf16_t* rowp = base + (size_t)((row >> 13) * LP + PADF + NMETA + tok) * ldc + col0;
;                 const float scr = sc * rstd[row];
;                 f32x4 c0 = {1.f, 1.f, 1.f, 1.f}, c1 = c0, s0 = {0.f, 0.f, 0.f, 0.f}, s1 = s0;
;                 if (dorope) {
;                     const int pos = NMETA + tok;
;                     if (fq < 2) { c0 = *(const f32x4*)(ropec + pos * 8); c1 = *(const f32x4*)(ropec + pos * 8 + 4); s0 = *(const f32x4*)(ropes + pos * 8); s1 = *(const f32x4*)(ropes + pos * 8 + 4); }
;                 }
; #pragma unroll
;                 for (int bj = 0; bj < 2; ++bj) {
;                     f32x4 v0 = acc[ai][bj][m][0] * scr, v1 = acc[ai][bj][m][1] * scr;
;                     if (dorope) {
;                         f32x4 p0, p1;
; #pragma unroll
;                         for (int e = 0; e < 4; ++e) { p0[e] = __shfl_xor(v0[e], 16); p1[e] = __shfl_xor(v1[e], 16); }
;                         v0 = v0 * c0 + (p0 * s0) * sgn; v1 = v1 * c1 + (p1 * s1) * sgn;
.LBB0_365:
	v_cvt_pk_bf16_f32 v90, v90, v91
	v_cvt_pk_bf16_f32 v91, v92, v93
	v_cvt_pk_bf16_f32 v92, v86, v87
	v_or_b32_e32 v86, 48, v166
	v_cvt_pk_bf16_f32 v93, v88, v89
	v_ashrrev_i32_e32 v87, 31, v86
	global_store_dwordx4 v[94:95], v[90:93], off offset:256
	v_lshl_add_u64 v[86:87], v[86:87], 2, s[72:73]
	v_mov_b32_e32 v102, v226
	s_movk_i32 s0, 0x1fff
	v_bitop3_b32 v106, v166, s0, 48 bitop3:0xc8
	v_mov_b32_e32 v98, 0
	v_mov_b32_e32 v90, 1.0
	v_mov_b32_e32 v91, 1.0
	v_mov_b32_e32 v92, 1.0
	v_mov_b32_e32 v93, 1.0
	v_mov_b32_e32 v86, 1.0
	v_mov_b32_e32 v87, 1.0
	v_mov_b32_e32 v88, 1.0
	v_mov_b32_e32 v89, 1.0
	v_mov_b32_e32 v99, 0
	v_mov_b32_e32 v100, 0
	v_mov_b32_e32 v101, 0
	v_mov_b32_e32 v94, 0
	v_mov_b32_e32 v95, 0
	v_mov_b32_e32 v96, 0
	v_mov_b32_e32 v97, 0
	s_and_saveexec_b64 s[20:21], s[30:31]
	s_cbranch_execz .LBB0_367
	v_readlane_b32 s0, v253, 20
	v_lshl_add_u32 v94, v106, 5, v220
	v_readlane_b32 s1, v253, 21
	s_nop 4
	global_load_dwordx4 v[90:93], v94, s[0:1]
	global_load_dwordx4 v[86:89], v94, s[0:1] offset:16
	v_readlane_b32 s0, v253, 22
	v_readlane_b32 s1, v253, 23
	s_nop 4
	global_load_dwordx4 v[98:101], v94, s[0:1]
	s_nop 0
	global_load_dwordx4 v[94:97], v94, s[0:1] offset:16
	s_waitcnt vmcnt(0)
.LBB0_367:
	s_or_b64 exec, exec, s[20:21]
	v_mul_f32_e32 v102, s19, v102
	v_pk_mul_f32 v[84:85], v[84:85], v[102:103] op_sel_hi:[1,0]
	v_pk_mul_f32 v[82:83], v[82:83], v[102:103] op_sel_hi:[1,0]
	v_pk_mul_f32 v[80:81], v[80:81], v[102:103] op_sel_hi:[1,0]
	s_and_b64 vcc, exec, s[46:47]
	v_pk_mul_f32 v[104:105], v[78:79], v[102:103] op_sel_hi:[1,0]
	s_cbranch_vccnz .LBB0_369
	v_and_b32_e32 v79, 64, v218
	v_xor_b32_e32 v78, 16, v218
	v_add_u32_e32 v79, 64, v79
	v_cmp_lt_i32_e32 vcc, v78, v79
	s_nop 1
	v_cndmask_b32_e32 v78, v218, v78, vcc
	v_lshlrev_b32_e32 v103, 2, v78
	ds_bpermute_b32 v78, v103, v82
	ds_bpermute_b32 v79, v103, v83
	ds_bpermute_b32 v108, v103, v104
	ds_bpermute_b32 v110, v103, v84
	ds_bpermute_b32 v111, v103, v85
	ds_bpermute_b32 v109, v103, v105
	ds_bpermute_b32 v112, v103, v80
	ds_bpermute_b32 v113, v103, v81
	s_waitcnt lgkmcnt(6)
	v_pk_mul_f32 v[78:79], v[98:99], v[78:79]
	s_waitcnt lgkmcnt(3)
	v_pk_mul_f32 v[110:111], v[100:101], v[110:111]
	v_pk_mul_f32 v[78:79], v[156:157], v[78:79]
	s_waitcnt lgkmcnt(2)
	v_pk_mul_f32 v[108:109], v[94:95], v[108:109]
	v_pk_fma_f32 v[82:83], v[82:83], v[90:91], v[78:79]
	s_waitcnt lgkmcnt(0)
	v_pk_mul_f32 v[78:79], v[96:97], v[112:113]
	v_pk_mul_f32 v[110:111], v[158:159], v[110:111]
	v_pk_mul_f32 v[108:109], v[156:157], v[108:109]
	v_pk_mul_f32 v[78:79], v[158:159], v[78:79]
	v_pk_fma_f32 v[84:85], v[84:85], v[92:93], v[110:111]
	v_pk_fma_f32 v[80:81], v[80:81], v[88:89], v[78:79]
	v_pk_fma_f32 v[104:105], v[104:105], v[86:87], v[108:109]

;     __device__ __forceinline__ void operator()(const pg8::f32x4 (&acc)[2][2][4][2], const pg8::Unit& u, int wr, int wc, int fr, int fq) const {
;     ...
;                 const int row = row0 + ai * 128 + m * 16;
;                 const int tok = row & (SEQ - 1);
;                 bf16_t* rowp = base + (size_t)((row >> 13) * LP + PADF + NMETA + tok) * ldc + col0;
;                 const float scr = sc * rstd[row];
;                 f32x4 c0 = {1.f, 1.f, 1.f, 1.f}, c1 = c0, s0 = {0.f, 0.f, 0.f, 0.f}, s1 = s0;
;                 if (dorope) {
;                     const int pos = NMETA + tok;
;                     if (fq < 2) { c0 = *(const f32x4*)(ropec + pos * 8); c1 = *(const f32x4*)(ropec + pos * 8 + 4); s0 = *(const f32x4*)(ropes + pos * 8); s1 = *(const f32x4*)(ropes + pos * 8 + 4); }
;                 }
; #pragma unroll
;                 for (int bj = 0; bj < 2; ++bj) {
;                     f32x4 v0 = acc[ai][bj][m][0] * scr, v1 = acc[ai][bj][m][1] * scr;
;                     if (dorope) {
;                         f32x4 p0, p1;
; #pragma unroll
;                         for (int e = 0; e < 4; ++e) { p0[e] = __shfl_xor(v0[e], 16); p1[e] = __shfl_xor(v1[e], 16); }
;                         v0 = v0 * c0 + (p0 * s0) * sgn; v1 = v1 * c1 + (p1 * s1) * sgn;
.LBB0_375:
	v_add_u32_e32 v86, 0x80, v166
	v_cvt_pk_bf16_f32 v74, v74, v75
	v_cvt_pk_bf16_f32 v75, v76, v77
	v_cvt_pk_bf16_f32 v76, v70, v71
	v_cvt_pk_bf16_f32 v77, v72, v73
	v_ashrrev_i32_e32 v87, 31, v86
	global_store_dwordx4 v[78:79], v[74:77], off offset:256
	v_lshl_add_u64 v[70:71], v[86:87], 2, s[72:73]
	v_mov_b32_e32 v88, v227
	v_and_b32_e32 v87, 0x1fcf, v86
	v_mov_b32_e32 v82, 0
	v_mov_b32_e32 v74, 1.0
	v_mov_b32_e32 v75, 1.0
	v_mov_b32_e32 v76, 1.0
	v_mov_b32_e32 v77, 1.0
	v_mov_b32_e32 v70, 1.0
	v_mov_b32_e32 v71, 1.0
	v_mov_b32_e32 v72, 1.0
	v_mov_b32_e32 v73, 1.0
	v_mov_b32_e32 v83, 0
	v_mov_b32_e32 v84, 0
	v_mov_b32_e32 v85, 0
	v_mov_b32_e32 v78, 0
	v_mov_b32_e32 v79, 0
	v_mov_b32_e32 v80, 0
	v_mov_b32_e32 v81, 0
	s_and_saveexec_b64 s[20:21], s[30:31]
	s_cbranch_execz .LBB0_377
	v_readlane_b32 s0, v253, 20
	v_lshl_or_b32 v78, v87, 5, v220
	v_readlane_b32 s1, v253, 21
	s_nop 4
	global_load_dwordx4 v[74:77], v78, s[0:1]
	global_load_dwordx4 v[70:73], v78, s[0:1] offset:16
	v_readlane_b32 s0, v253, 22
	v_readlane_b32 s1, v253, 23
	s_nop 4
	global_load_dwordx4 v[82:85], v78, s[0:1]
	s_nop 0
	global_load_dwordx4 v[78:81], v78, s[0:1] offset:16
	s_waitcnt vmcnt(0)
.LBB0_377:
	s_or_b64 exec, exec, s[20:21]
	v_mul_f32_e32 v88, s19, v88
	v_pk_mul_f32 v[68:69], v[68:69], v[88:89] op_sel_hi:[1,0]
	v_pk_mul_f32 v[66:67], v[66:67], v[88:89] op_sel_hi:[1,0]
	v_pk_mul_f32 v[64:65], v[64:65], v[88:89] op_sel_hi:[1,0]
	s_and_b64 vcc, exec, s[46:47]
	v_pk_mul_f32 v[90:91], v[62:63], v[88:89] op_sel_hi:[1,0]
	s_cbranch_vccnz .LBB0_379
	v_and_b32_e32 v63, 64, v218
	v_xor_b32_e32 v62, 16, v218
	v_add_u32_e32 v63, 64, v63
	v_cmp_lt_i32_e32 vcc, v62, v63
	s_nop 1
	v_cndmask_b32_e32 v62, v218, v62, vcc
	v_lshlrev_b32_e32 v89, 2, v62
	ds_bpermute_b32 v62, v89, v66
	ds_bpermute_b32 v63, v89, v67
	ds_bpermute_b32 v92, v89, v90
	ds_bpermute_b32 v94, v89, v68
	ds_bpermute_b32 v95, v89, v69
	ds_bpermute_b32 v93, v89, v91
	ds_bpermute_b32 v96, v89, v64
	ds_bpermute_b32 v97, v89, v65
	s_waitcnt lgkmcnt(6)
	v_pk_mul_f32 v[62:63], v[82:83], v[62:63]
	s_waitcnt lgkmcnt(3)
	v_pk_mul_f32 v[94:95], v[84:85], v[94:95]
	v_pk_mul_f32 v[62:63], v[156:157], v[62:63]
	s_waitcnt lgkmcnt(2)
	v_pk_mul_f32 v[92:93], v[78:79], v[92:93]
	v_pk_fma_f32 v[66:67], v[66:67], v[74:75], v[62:63]
	s_waitcnt lgkmcnt(0)
	v_pk_mul_f32 v[62:63], v[80:81], v[96:97]
	v_pk_mul_f32 v[94:95], v[158:159], v[94:95]
	v_pk_mul_f32 v[92:93], v[156:157], v[92:93]
	v_pk_mul_f32 v[62:63], v[158:159], v[62:63]
	v_pk_fma_f32 v[68:69], v[68:69], v[76:77], v[94:95]
	v_pk_fma_f32 v[64:65], v[64:65], v[72:73], v[62:63]
	v_pk_fma_f32 v[90:91], v[90:91], v[70:71], v[92:93]

;     __device__ __forceinline__ void operator()(const pg8::f32x4 (&acc)[2][2][4][2], const pg8::Unit& u, int wr, int wc, int fr, int fq) const {
;     ...
;                 const int row = row0 + ai * 128 + m * 16;
;                 const int tok = row & (SEQ - 1);
;                 bf16_t* rowp = base + (size_t)((row >> 13) * LP + PADF + NMETA + tok) * ldc + col0;
;                 const float scr = sc * rstd[row];
;                 f32x4 c0 = {1.f, 1.f, 1.f, 1.f}, c1 = c0, s0 = {0.f, 0.f, 0.f, 0.f}, s1 = s0;
;                 if (dorope) {
;                     const int pos = NMETA + tok;
;                     if (fq < 2) { c0 = *(const f32x4*)(ropec + pos * 8); c1 = *(const f32x4*)(ropec + pos * 8 + 4); s0 = *(const f32x4*)(ropes + pos * 8); s1 = *(const f32x4*)(ropes + pos * 8 + 4); }
;                 }
; #pragma unroll
;                 for (int bj = 0; bj < 2; ++bj) {
;                     f32x4 v0 = acc[ai][bj][m][0] * scr, v1 = acc[ai][bj][m][1] * scr;
;                     if (dorope) {
;                         f32x4 p0, p1;
; #pragma unroll
;                         for (int e = 0; e < 4; ++e) { p0[e] = __shfl_xor(v0[e], 16); p1[e] = __shfl_xor(v1[e], 16); }
;                         v0 = v0 * c0 + (p0 * s0) * sgn; v1 = v1 * c1 + (p1 * s1) * sgn;
.LBB0_385:
	v_cvt_pk_bf16_f32 v58, v58, v59
	v_cvt_pk_bf16_f32 v59, v60, v61
	v_cvt_pk_bf16_f32 v60, v54, v55
	v_add_u32_e32 v54, 0x90, v166
	v_cvt_pk_bf16_f32 v61, v56, v57
	v_ashrrev_i32_e32 v55, 31, v54
	global_store_dwordx4 v[62:63], v[58:61], off offset:256
	v_lshl_add_u64 v[56:57], v[54:55], 2, s[72:73]
	v_mov_b32_e32 v70, v228
	v_and_b32_e32 v74, 0x1fdf, v54
	v_mov_b32_e32 v66, 0
	v_mov_b32_e32 v58, 1.0
	v_mov_b32_e32 v59, 1.0
	v_mov_b32_e32 v60, 1.0
	v_mov_b32_e32 v61, 1.0
	v_mov_b32_e32 v54, 1.0
	v_mov_b32_e32 v55, 1.0
	v_mov_b32_e32 v56, 1.0
	v_mov_b32_e32 v57, 1.0
	v_mov_b32_e32 v67, 0
	v_mov_b32_e32 v68, 0
	v_mov_b32_e32 v69, 0
	v_mov_b32_e32 v62, 0
	v_mov_b32_e32 v63, 0
	v_mov_b32_e32 v64, 0
	v_mov_b32_e32 v65, 0
	s_and_saveexec_b64 s[20:21], s[30:31]
	s_cbranch_execz .LBB0_387
	v_readlane_b32 s0, v253, 20
	v_lshl_add_u32 v62, v74, 5, v220
	v_readlane_b32 s1, v253, 21
	s_nop 4
	global_load_dwordx4 v[58:61], v62, s[0:1]
	global_load_dwordx4 v[54:57], v62, s[0:1] offset:16
	v_readlane_b32 s0, v253, 22
	v_readlane_b32 s1, v253, 23
	s_nop 4
	global_load_dwordx4 v[66:69], v62, s[0:1]
	s_nop 0
	global_load_dwordx4 v[62:65], v62, s[0:1] offset:16
	s_waitcnt vmcnt(0)
.LBB0_387:
	s_or_b64 exec, exec, s[20:21]
	v_mul_f32_e32 v70, s19, v70
	v_pk_mul_f32 v[52:53], v[52:53], v[70:71] op_sel_hi:[1,0]
	v_pk_mul_f32 v[50:51], v[50:51], v[70:71] op_sel_hi:[1,0]
	v_pk_mul_f32 v[48:49], v[48:49], v[70:71] op_sel_hi:[1,0]
	s_and_b64 vcc, exec, s[46:47]
	v_pk_mul_f32 v[72:73], v[46:47], v[70:71] op_sel_hi:[1,0]
	s_cbranch_vccnz .LBB0_389
	v_and_b32_e32 v47, 64, v218
	v_xor_b32_e32 v46, 16, v218
	v_add_u32_e32 v47, 64, v47
	v_cmp_lt_i32_e32 vcc, v46, v47
	s_nop 1
	v_cndmask_b32_e32 v46, v218, v46, vcc
	v_lshlrev_b32_e32 v71, 2, v46
	ds_bpermute_b32 v46, v71, v50
	ds_bpermute_b32 v47, v71, v51
	ds_bpermute_b32 v76, v71, v72
	ds_bpermute_b32 v78, v71, v52
	ds_bpermute_b32 v79, v71, v53
	ds_bpermute_b32 v77, v71, v73
	ds_bpermute_b32 v80, v71, v48
	ds_bpermute_b32 v81, v71, v49
	s_waitcnt lgkmcnt(6)
	v_pk_mul_f32 v[46:47], v[66:67], v[46:47]
	s_waitcnt lgkmcnt(3)
	v_pk_mul_f32 v[78:79], v[68:69], v[78:79]
	v_pk_mul_f32 v[46:47], v[156:157], v[46:47]
	s_waitcnt lgkmcnt(2)
	v_pk_mul_f32 v[76:77], v[62:63], v[76:77]
	v_pk_fma_f32 v[50:51], v[50:51], v[58:59], v[46:47]
	s_waitcnt lgkmcnt(0)
	v_pk_mul_f32 v[46:47], v[64:65], v[80:81]
	v_pk_mul_f32 v[78:79], v[158:159], v[78:79]
	v_pk_mul_f32 v[76:77], v[156:157], v[76:77]
	v_pk_mul_f32 v[46:47], v[158:159], v[46:47]
	v_pk_fma_f32 v[52:53], v[52:53], v[60:61], v[78:79]
	v_pk_fma_f32 v[48:49], v[48:49], v[56:57], v[46:47]
	v_pk_fma_f32 v[72:73], v[72:73], v[54:55], v[76:77]

;     __device__ __forceinline__ void operator()(const pg8::f32x4 (&acc)[2][2][4][2], const pg8::Unit& u, int wr, int wc, int fr, int fq) const {
;     ...
;                 const int row = row0 + ai * 128 + m * 16;
;                 const int tok = row & (SEQ - 1);
;                 bf16_t* rowp = base + (size_t)((row >> 13) * LP + PADF + NMETA + tok) * ldc + col0;
;                 const float scr = sc * rstd[row];
;                 f32x4 c0 = {1.f, 1.f, 1.f, 1.f}, c1 = c0, s0 = {0.f, 0.f, 0.f, 0.f}, s1 = s0;
;                 if (dorope) {
;                     const int pos = NMETA + tok;
;                     if (fq < 2) { c0 = *(const f32x4*)(ropec + pos * 8); c1 = *(const f32x4*)(ropec + pos * 8 + 4); s0 = *(const f32x4*)(ropes + pos * 8); s1 = *(const f32x4*)(ropes + pos * 8 + 4); }
;                 }
; #pragma unroll
;                 for (int bj = 0; bj < 2; ++bj) {
;                     f32x4 v0 = acc[ai][bj][m][0] * scr, v1 = acc[ai][bj][m][1] * scr;
;                     if (dorope) {
;                         f32x4 p0, p1;
; #pragma unroll
;                         for (int e = 0; e < 4; ++e) { p0[e] = __shfl_xor(v0[e], 16); p1[e] = __shfl_xor(v1[e], 16); }
;                         v0 = v0 * c0 + (p0 * s0) * sgn; v1 = v1 * c1 + (p1 * s1) * sgn;
.LBB0_395:
	v_cvt_pk_bf16_f32 v42, v42, v43
	v_cvt_pk_bf16_f32 v43, v44, v45
	v_cvt_pk_bf16_f32 v44, v38, v39
	v_add_u32_e32 v38, 0xa0, v166
	v_cvt_pk_bf16_f32 v45, v40, v41
	v_ashrrev_i32_e32 v39, 31, v38
	global_store_dwordx4 v[46:47], v[42:45], off offset:256
	v_lshl_add_u64 v[40:41], v[38:39], 2, s[72:73]
	v_mov_b32_e32 v54, v229
	v_and_b32_e32 v58, 0x1fef, v38
	v_mov_b32_e32 v50, 0
	v_mov_b32_e32 v42, 1.0
	v_mov_b32_e32 v43, 1.0
	v_mov_b32_e32 v44, 1.0
	v_mov_b32_e32 v45, 1.0
	v_mov_b32_e32 v38, 1.0
	v_mov_b32_e32 v39, 1.0
	v_mov_b32_e32 v40, 1.0
	v_mov_b32_e32 v41, 1.0
	v_mov_b32_e32 v51, 0
	v_mov_b32_e32 v52, 0
	v_mov_b32_e32 v53, 0
	v_mov_b32_e32 v46, 0
	v_mov_b32_e32 v47, 0
	v_mov_b32_e32 v48, 0
	v_mov_b32_e32 v49, 0
	s_and_saveexec_b64 s[20:21], s[30:31]
	s_cbranch_execz .LBB0_397
	v_readlane_b32 s0, v253, 20
	v_lshl_or_b32 v46, v58, 5, v220
	v_readlane_b32 s1, v253, 21
	s_nop 4
	global_load_dwordx4 v[42:45], v46, s[0:1]
	global_load_dwordx4 v[38:41], v46, s[0:1] offset:16
	v_readlane_b32 s0, v253, 22
	v_readlane_b32 s1, v253, 23
	s_nop 4
	global_load_dwordx4 v[50:53], v46, s[0:1]
	s_nop 0
	global_load_dwordx4 v[46:49], v46, s[0:1] offset:16
	s_waitcnt vmcnt(0)
.LBB0_397:
	s_or_b64 exec, exec, s[20:21]
	v_mul_f32_e32 v54, s19, v54
	v_pk_mul_f32 v[36:37], v[36:37], v[54:55] op_sel_hi:[1,0]
	v_pk_mul_f32 v[34:35], v[34:35], v[54:55] op_sel_hi:[1,0]
	v_pk_mul_f32 v[32:33], v[32:33], v[54:55] op_sel_hi:[1,0]
	s_and_b64 vcc, exec, s[46:47]
	v_pk_mul_f32 v[56:57], v[30:31], v[54:55] op_sel_hi:[1,0]
	s_cbranch_vccnz .LBB0_399
	v_and_b32_e32 v31, 64, v218
	v_xor_b32_e32 v30, 16, v218
	v_add_u32_e32 v31, 64, v31
	v_cmp_lt_i32_e32 vcc, v30, v31
	s_nop 1
	v_cndmask_b32_e32 v30, v218, v30, vcc
	v_lshlrev_b32_e32 v55, 2, v30
	ds_bpermute_b32 v30, v55, v34
	ds_bpermute_b32 v31, v55, v35
	ds_bpermute_b32 v60, v55, v56
	ds_bpermute_b32 v62, v55, v36
	ds_bpermute_b32 v63, v55, v37
	ds_bpermute_b32 v61, v55, v57
	ds_bpermute_b32 v64, v55, v32
	ds_bpermute_b32 v65, v55, v33
	s_waitcnt lgkmcnt(6)
	v_pk_mul_f32 v[30:31], v[50:51], v[30:31]
	s_waitcnt lgkmcnt(3)
	v_pk_mul_f32 v[62:63], v[52:53], v[62:63]
	v_pk_mul_f32 v[30:31], v[156:157], v[30:31]
	s_waitcnt lgkmcnt(2)
	v_pk_mul_f32 v[60:61], v[46:47], v[60:61]
	v_pk_fma_f32 v[34:35], v[34:35], v[42:43], v[30:31]
	s_waitcnt lgkmcnt(0)
	v_pk_mul_f32 v[30:31], v[48:49], v[64:65]
	v_pk_mul_f32 v[62:63], v[158:159], v[62:63]
	v_pk_mul_f32 v[60:61], v[156:157], v[60:61]
	v_pk_mul_f32 v[30:31], v[158:159], v[30:31]
	v_pk_fma_f32 v[36:37], v[36:37], v[44:45], v[62:63]
	v_pk_fma_f32 v[32:33], v[32:33], v[40:41], v[30:31]
	v_pk_fma_f32 v[56:57], v[56:57], v[38:39], v[60:61]

;     __device__ __forceinline__ void operator()(const pg8::f32x4 (&acc)[2][2][4][2], const pg8::Unit& u, int wr, int wc, int fr, int fq) const {
;     ...
;                 const int row = row0 + ai * 128 + m * 16;
;                 const int tok = row & (SEQ - 1);
;                 bf16_t* rowp = base + (size_t)((row >> 13) * LP + PADF + NMETA + tok) * ldc + col0;
;                 const float scr = sc * rstd[row];
;                 f32x4 c0 = {1.f, 1.f, 1.f, 1.f}, c1 = c0, s0 = {0.f, 0.f, 0.f, 0.f}, s1 = s0;
;                 if (dorope) {
;                     const int pos = NMETA + tok;
;                     if (fq < 2) { c0 = *(const f32x4*)(ropec + pos * 8); c1 = *(const f32x4*)(ropec + pos * 8 + 4); s0 = *(const f32x4*)(ropes + pos * 8); s1 = *(const f32x4*)(ropes + pos * 8 + 4); }
;                 }
; #pragma unroll
;                 for (int bj = 0; bj < 2; ++bj) {
;                     f32x4 v0 = acc[ai][bj][m][0] * scr, v1 = acc[ai][bj][m][1] * scr;
;                     if (dorope) {
;                         f32x4 p0, p1;
; #pragma unroll
;                         for (int e = 0; e < 4; ++e) { p0[e] = __shfl_xor(v0[e], 16); p1[e] = __shfl_xor(v1[e], 16); }
;                         v0 = v0 * c0 + (p0 * s0) * sgn; v1 = v1 * c1 + (p1 * s1) * sgn;
.LBB0_405:
	v_cvt_pk_bf16_f32 v26, v26, v27
	v_cvt_pk_bf16_f32 v27, v28, v29
	v_cvt_pk_bf16_f32 v28, v22, v23
	v_add_u32_e32 v22, 0xb0, v166
	v_cvt_pk_bf16_f32 v29, v24, v25
	v_ashrrev_i32_e32 v23, 31, v22
	global_store_dwordx4 v[30:31], v[26:29], off offset:256
	v_lshl_add_u64 v[24:25], v[22:23], 2, s[72:73]
	v_mov_b32_e32 v38, v230
	v_and_b32_e32 v42, 0x1fff, v22
	v_mov_b32_e32 v34, 0
	v_mov_b32_e32 v26, 1.0
	v_mov_b32_e32 v27, 1.0
	v_mov_b32_e32 v28, 1.0
	v_mov_b32_e32 v29, 1.0
	v_mov_b32_e32 v22, 1.0
	v_mov_b32_e32 v23, 1.0
	v_mov_b32_e32 v24, 1.0
	v_mov_b32_e32 v25, 1.0
	v_mov_b32_e32 v35, 0
	v_mov_b32_e32 v36, 0
	v_mov_b32_e32 v37, 0
	v_mov_b32_e32 v30, 0
	v_mov_b32_e32 v31, 0
	v_mov_b32_e32 v32, 0
	v_mov_b32_e32 v33, 0
	s_and_saveexec_b64 s[20:21], s[30:31]
	s_cbranch_execz .LBB0_407
	v_readlane_b32 s0, v253, 20
	v_lshl_add_u32 v30, v42, 5, v220
	v_readlane_b32 s1, v253, 21
	s_nop 4
	global_load_dwordx4 v[26:29], v30, s[0:1]
	global_load_dwordx4 v[22:25], v30, s[0:1] offset:16
	v_readlane_b32 s0, v253, 22
	v_readlane_b32 s1, v253, 23
	s_nop 4
	global_load_dwordx4 v[34:37], v30, s[0:1]
	s_nop 0
	global_load_dwordx4 v[30:33], v30, s[0:1] offset:16
	s_waitcnt vmcnt(0)
.LBB0_407:
	s_or_b64 exec, exec, s[20:21]
	v_mul_f32_e32 v38, s19, v38
	v_pk_mul_f32 v[20:21], v[20:21], v[38:39] op_sel_hi:[1,0]
	v_pk_mul_f32 v[18:19], v[18:19], v[38:39] op_sel_hi:[1,0]
	v_pk_mul_f32 v[12:13], v[12:13], v[38:39] op_sel_hi:[1,0]
	s_and_b64 vcc, exec, s[46:47]
	v_pk_mul_f32 v[40:41], v[10:11], v[38:39] op_sel_hi:[1,0]
	s_mov_b32 s31, 0xbfb8aa3b
	s_cbranch_vccnz .LBB0_409
	v_and_b32_e32 v11, 64, v218
	v_xor_b32_e32 v10, 16, v218
	v_add_u32_e32 v11, 64, v11
	v_cmp_lt_i32_e32 vcc, v10, v11
	s_nop 1
	v_cndmask_b32_e32 v10, v218, v10, vcc
	v_lshlrev_b32_e32 v39, 2, v10
	ds_bpermute_b32 v10, v39, v18
	ds_bpermute_b32 v11, v39, v19
	ds_bpermute_b32 v44, v39, v40
	ds_bpermute_b32 v46, v39, v20
	ds_bpermute_b32 v47, v39, v21
	ds_bpermute_b32 v45, v39, v41
	ds_bpermute_b32 v48, v39, v12
	ds_bpermute_b32 v49, v39, v13
	s_waitcnt lgkmcnt(6)
	v_pk_mul_f32 v[10:11], v[34:35], v[10:11]
	s_waitcnt lgkmcnt(3)
	v_pk_mul_f32 v[46:47], v[36:37], v[46:47]
	v_pk_mul_f32 v[10:11], v[156:157], v[10:11]
	s_waitcnt lgkmcnt(2)
	v_pk_mul_f32 v[44:45], v[30:31], v[44:45]
	v_pk_fma_f32 v[18:19], v[18:19], v[26:27], v[10:11]
	s_waitcnt lgkmcnt(0)
	v_pk_mul_f32 v[10:11], v[32:33], v[48:49]
	v_pk_mul_f32 v[46:47], v[158:159], v[46:47]
	v_pk_mul_f32 v[44:45], v[156:157], v[44:45]
	v_pk_mul_f32 v[10:11], v[158:159], v[10:11]
	v_pk_fma_f32 v[20:21], v[20:21], v[28:29], v[46:47]
	v_pk_fma_f32 v[12:13], v[12:13], v[24:25], v[10:11]
	v_pk_fma_f32 v[40:41], v[40:41], v[22:23], v[44:45]

; template <bool FOX> ...
;     const int tid = opaque_tid(), lane = tid & 63, wid = rfl(tid >> 6), stream = wid >> 2, wq = wid & 3, l31 = lane & 31, hi = lane >> 5;
;     constexpr int NCB = FOX ? 2 : 4;
;     const size_t rowb = (size_t)b * LP;
;     const int q0 = j * 128, qloc128 = 32 * wq + l31, qrow = q0 + qloc128;
;     const int tq = 2 * j + (wq >> 1);
;     const int NT = 2 * j + 1;
;     bf16x8 qf[4];
;     { const bf16_t* qp = QALL + (rowb + qrow) * DM + (FOX ? 512 : 0) + 128 * g + 64 * stream + 8 * hi;
; #pragma unroll
;       for (int s = 0; s < 4; ++s) qf[s] = *(const bf16x8*)(qp + 16 * s); }
;     float cq2 = 0.f;
;     if (FOX) cq2 = CF[(rowb + qrow) * 8 + 2 * g + stream] * LOG2E;
;     const int r4 = lane >> 4, c16 = lane & 15;
;     const int chA = c16 ^ ((r4 << 2) | ((2 * wid) & 3)), chB = c16 ^ ((r4 << 2) | ((2 * wid + 1) & 3));
;     const bf16_t* kgA = K + (rowb + 8 * wid + r4) * 512 + 128 * g + 8 * chA;
;     const bf16_t* kgB = K + (rowb + 8 * wid + 4 + r4) * 512 + 128 * g + 8 * chB;
;     const bf16_t* vgA = V + (rowb + 8 * wid + r4) * 512 + 128 * g + 8 * chA;
;     const bf16_t* vgB = V + (rowb + 8 * wid + 4 + r4) * 512 + 128 * g + 8 * chB;
;     const float* cfg = CF + (rowb + lane) * 8 + 2 * g + (wid & 1);
;     ...
;     const unsigned krow = (l31 & ~12u) | ((l31 & 4u) << 1) | ((l31 & 8u) >> 1);
;     unsigned koff[4];
; #pragma unroll
;     for (int s = 0; s < 4; ++s) koff[s] = offb(krow, 8 * stream + 2 * s + hi);
;     unsigned voff[NCB][2];
; #pragma unroll
;     for (int cb = 0; cb < NCB; ++cb)
; #pragma unroll
;         for (int t = 0; t < 2; ++t) voff[cb][t] = 16384u + tr_addr(lane, FOX ? 2 * stream + cb : cb, 0, t);
;     f32x16 o[NCB];
; #pragma unroll
;     for (int cb = 0; cb < NCB; ++cb)
; #pragma unroll
;         for (int r = 0; r < 16; ++r) o[cb][r] = 0.f;
;     float lsum = 0.f;
;     const int qloc64 = 32 * (wq & 1) + l31;
;     constexpr float THR = 96.0f, SKIP_T = 40.0f;
;     float ub = 0.f, qb;
;     {
;         float q1 = 0.f;
; #pragma unroll
; __device__ __forceinline__ void attn_phase(LAS unsigned char* lds, const Args& a, int layer, unsigned* counters) {
;     ...
;         const int q = u / 260, i = u % 260;
;         if (i < 130) { const int j = NBLK - 1 - (i >> 1), bh = q + 8 * (i & 1); attn_unit<false>(lds, bh >> 2, bh & 3, j, QALL, KD, VD, GD, CF, a.subln + layer * 128, lam, oml, 1.42f * kinfd4[bh & 3], AO); }
.LBB0_538:
	s_and_b64 vcc, exec, s[2:3]
	s_cbranch_vccz .LBB0_476
	s_cmpk_gt_u32 s35, 0x40
	s_cselect_b32 s1, 8, 0
	s_cselect_b32 s22, 0x41, 0
	s_add_i32 s1, s1, s6
	v_mov_b32_e32 v17, v210
	s_lshr_b32 s20, s1, 2
	s_sub_i32 s22, s35, s22
	v_readfirstlane_b32 s1, v17
	s_ashr_i32 s21, s1, 6
	s_sub_i32 s0, 64, s22
	s_and_b32 s3, s21, 3
	s_lshl_b32 s4, s0, 7
	s_lshl_b32 s5, s3, 5
	s_or_b32 s4, s5, s4
	v_and_or_b32 v192, v17, 31, s4
	v_mov_b32_e32 v193, v0
	v_mad_u64_u32 v[194:195], s[4:5], s20, v222, v[192:193]
	v_readlane_b32 s4, v253, 30
	s_ashr_i32 s2, s1, 8
	v_lshlrev_b64 v[2:3], 11, v[194:195]
	v_readlane_b32 s5, v253, 31
	s_lshl_b32 s16, s34, 8
	v_bfe_u32 v1, v17, 5, 1
	v_lshl_add_u64 v[2:3], s[4:5], 0, v[2:3]
	s_lshl_b32 s4, s2, 6
	v_lshl_add_u64 v[2:3], v[2:3], 0, s[16:17]
	s_ashr_i32 s5, s4, 31
	v_lshl_add_u64 v[2:3], s[4:5], 1, v[2:3]
	v_lshlrev_b32_e32 v14, 4, v1
	v_mov_b32_e32 v15, v0
	v_lshl_add_u64 v[18:19], v[2:3], 0, v[14:15]
	global_load_dwordx4 v[2:5], v[18:19], off
	global_load_dwordx4 v[6:9], v[18:19], off offset:32
	global_load_dwordx4 v[10:13], v[18:19], off offset:64
	global_load_dwordx4 v[144:147], v[18:19], off offset:96
	v_bfe_u32 v15, v17, 4, 2
	s_lshl_b32 s4, s21, 1
	v_and_b32_e32 v18, 15, v17
	v_lshlrev_b32_e32 v19, 2, v15
	s_and_b32 s4, s4, 2
	v_or_b32_e32 v20, s4, v19
	v_bitop3_b32 v28, s4, v18, v19 bitop3:0x36
	s_lshl_b32 s4, s21, 3
	s_mul_i32 s6, s20, 0x2080
	s_ashr_i32 s5, s4, 31
	s_mul_hi_u32 s1, s20, 0x2080
	s_add_u32 s4, s6, s4
	s_addc_u32 s1, s1, s5
	v_bitop3_b32 v30, v20, v18, 1 bitop3:0x36
	v_or_b32_e32 v18, s4, v15
	v_mov_b32_e32 v19, s1
	v_readlane_b32 s4, v253, 10
	v_lshlrev_b64 v[18:19], 10, v[18:19]
	v_readlane_b32 s5, v253, 11
	v_lshl_add_u64 v[20:21], s[70:71], 0, v[18:19]
	v_or_b32_e32 v22, 0x1000, v18
	v_mov_b32_e32 v23, v19
	v_lshl_add_u64 v[18:19], s[4:5], 0, v[18:19]
	v_lshl_add_u64 v[24:25], s[70:71], 0, v[22:23]
	v_lshl_add_u64 v[26:27], v[18:19], 0, s[16:17]
	v_lshl_add_u64 v[18:19], s[4:5], 0, v[22:23]
	v_lshl_add_u64 v[22:23], v[20:21], 0, s[16:17]
	v_lshlrev_b32_e32 v28, 4, v28
	v_mov_b32_e32 v29, v0
	s_lshl_b32 s1, s21, 11
	v_lshl_add_u64 v[18:19], v[18:19], 0, s[16:17]
	v_lshl_add_u64 v[24:25], v[24:25], 0, s[16:17]
	v_lshlrev_b32_e32 v20, 4, v30
	v_mov_b32_e32 v21, v0
	v_lshl_add_u64 v[200:201], v[22:23], 0, v[28:29]
	s_add_i32 s24, s1, 0
	s_mov_b64 s[4:5], 0x10000
	v_lshl_add_u64 v[198:199], v[24:25], 0, v[20:21]
	v_lshl_add_u64 v[202:203], v[18:19], 0, v[20:21]
	v_lshl_add_u64 v[18:19], v[200:201], 0, s[4:5]
	s_mov_b32 m0, s24
	v_lshl_add_u64 v[196:197], v[26:27], 0, v[28:29]
	global_load_lds_dwordx4 v[18:19], off
	v_lshl_add_u64 v[18:19], v[198:199], 0, s[4:5]
	s_add_i32 m0, s24, 0x400
	s_waitcnt vmcnt(0)
	v_lshlrev_b32_e32 v15, 16, v2
	global_load_lds_dwordx4 v[18:19], off
	v_lshl_add_u64 v[18:19], v[196:197], 0, s[4:5]
	s_add_i32 m0, s24, 0x4000
	v_and_b32_e32 v22, 0xffff0000, v2
	global_load_lds_dwordx4 v[18:19], off
	v_lshl_add_u64 v[18:19], v[202:203], 0, s[4:5]
	s_add_i32 m0, s24, 0x4400
	v_add_f32_e64 v15, |v15|, |v22|
	global_load_lds_dwordx4 v[18:19], off
	v_lshlrev_b32_e32 v22, 16, v3
	v_add_f32_e64 v15, |v22|, v15
	v_and_b32_e32 v22, 0xffff0000, v3
	v_add_f32_e64 v15, |v22|, v15
	v_lshlrev_b32_e32 v22, 16, v4
	v_add_f32_e64 v15, |v22|, v15
	v_and_b32_e32 v22, 0xffff0000, v4
	v_add_f32_e64 v15, |v22|, v15
	v_lshlrev_b32_e32 v22, 16, v5
	v_add_f32_e64 v15, |v22|, v15
	v_and_b32_e32 v22, 0xffff0000, v5
	v_add_f32_e64 v15, |v22|, v15
	v_lshlrev_b32_e32 v22, 16, v6
	v_add_f32_e64 v15, |v22|, v15
	v_and_b32_e32 v22, 0xffff0000, v6
	v_add_f32_e64 v15, |v22|, v15
	v_lshlrev_b32_e32 v22, 16, v7
	v_add_f32_e64 v15, |v22|, v15
	v_and_b32_e32 v22, 0xffff0000, v7
	v_add_f32_e64 v15, |v22|, v15
	v_lshlrev_b32_e32 v22, 16, v8
	v_add_f32_e64 v15, |v22|, v15
	v_and_b32_e32 v22, 0xffff0000, v8
	v_add_f32_e64 v15, |v22|, v15
	v_lshlrev_b32_e32 v22, 16, v9
	v_add_f32_e64 v15, |v22|, v15
	v_and_b32_e32 v22, 0xffff0000, v9
	v_add_f32_e64 v15, |v22|, v15
	v_lshlrev_b32_e32 v22, 16, v10
	v_add_f32_e64 v15, |v22|, v15
	v_and_b32_e32 v22, 0xffff0000, v10
	v_add_f32_e64 v15, |v22|, v15
	v_lshlrev_b32_e32 v22, 16, v11
	v_add_f32_e64 v15, |v22|, v15
	v_and_b32_e32 v22, 0xffff0000, v11
	v_add_f32_e64 v15, |v22|, v15
	v_lshlrev_b32_e32 v22, 16, v12
	v_add_f32_e64 v15, |v22|, v15
	v_and_b32_e32 v22, 0xffff0000, v12
	v_add_f32_e64 v15, |v22|, v15
	v_lshlrev_b32_e32 v22, 16, v13
	v_add_f32_e64 v15, |v22|, v15
	v_and_b32_e32 v22, 0xffff0000, v13
	v_add_f32_e64 v15, |v22|, v15
	v_lshlrev_b32_e32 v22, 16, v144
	v_add_f32_e64 v15, |v22|, v15
	v_and_b32_e32 v22, 0xffff0000, v144
	v_add_f32_e64 v15, |v22|, v15
	v_lshlrev_b32_e32 v22, 16, v145
	v_add_f32_e64 v15, |v22|, v15
	v_and_b32_e32 v22, 0xffff0000, v145
	v_add_f32_e64 v15, |v22|, v15
	v_lshlrev_b32_e32 v22, 16, v146
	v_add_f32_e64 v15, |v22|, v15
	v_and_b32_e32 v22, 0xffff0000, v146
	v_add_f32_e64 v15, |v22|, v15
	v_lshlrev_b32_e32 v22, 16, v147
	v_add_f32_e64 v15, |v22|, v15
	v_and_b32_e32 v22, 0xffff0000, v147
	v_add_f32_e64 v38, |v22|, v15
	v_mov_b32_e32 v39, v38
	s_cmp_lg_u32 s22, 64
	s_nop 0
	v_permlane32_swap_b32_e32 v38, v39
	s_mov_b64 s[4:5], -1
	s_cselect_b64 s[12:13], -1, 0
	s_cmp_eq_u32 s22, 64
	s_cbranch_scc1 .LBB0_541
	s_mov_b64 s[4:5], 0x20000
	s_add_i32 m0, s24, 0x8000
	v_lshl_add_u64 v[18:19], v[200:201], 0, s[4:5]
	global_load_lds_dwordx4 v[18:19], off
	v_lshl_add_u64 v[18:19], v[198:199], 0, s[4:5]
	s_add_i32 m0, s24, 0x8400
	s_nop 0
	global_load_lds_dwordx4 v[18:19], off
	v_lshl_add_u64 v[18:19], v[196:197], 0, s[4:5]
	s_add_i32 m0, s24, 0xc000
	s_nop 0
	global_load_lds_dwordx4 v[18:19], off
	v_lshl_add_u64 v[18:19], v[202:203], 0, s[4:5]
	s_add_i32 m0, s24, 0xc400
	s_mov_b64 s[4:5], 0
	global_load_lds_dwordx4 v[18:19], off
	s_waitcnt vmcnt(4) lgkmcnt(0)
	s_barrier

; template <bool FOX> ...
;     ...
;     bool wmore = (tq >= 1), first = true;
;     float mref = 0.f;
;     f32x16 negm;
; #pragma unroll
;     for (int r = 0; r < 16; ++r) negm[r] = 0.f;
;     bf16x8 pf[4];
; #pragma unroll
;     for (int s = 0; s < 4; ++s) pf[s] = (bf16x8){0, 0, 0, 0, 0, 0, 0, 0};
;     ...
;     int pbuf = 0, buf = 0;
.LBB0_560:
	v_add_f32_e32 v18, v22, v23
	v_add_f32_e32 v244, v17, v18
	s_and_b64 vcc, exec, s[6:7]
	s_mov_b32 s14, 0
	s_cbranch_vccnz .LBB0_586
	s_cmp_lt_u32 s21, 4
	s_cbranch_scc1 .Ldiff_noprio
	s_setprio 1
.Ldiff_noprio:
	s_lshl_b32 s7, s22, 1
	s_mov_b32 s6, 1
	s_mov_b32 s23, 0
	s_sub_i32 s18, 0, s7
	s_movk_i32 s19, 0xff80
	s_movk_i32 s16, 0x100
	v_mov_b32_e32 v97, v96
	v_mov_b32_e32 v98, v96
	v_mov_b32_e32 v99, v96
	v_mov_b32_e32 v100, v96
	v_mov_b32_e32 v101, v96
	v_mov_b32_e32 v102, v96
	v_mov_b32_e32 v103, v96
	v_mov_b32_e32 v104, v96
	v_mov_b32_e32 v105, v96
	v_mov_b32_e32 v106, v96
	v_mov_b32_e32 v107, v96
	v_mov_b32_e32 v108, v96
	v_mov_b32_e32 v109, v96
	v_mov_b32_e32 v110, v96
	v_mov_b32_e32 v111, v96

; #define ATT_WAIT_BAR(pending) do { if (pending) { if (FOX) asm volatile("s_waitcnt vmcnt(5) lgkmcnt(0)\n\ts_barrier" ::: "memory"); else asm volatile("s_waitcnt vmcnt(4) lgkmcnt(0)\n\ts_barrier" ::: "memory"); } \
;         else asm volatile("s_waitcnt vmcnt(0) lgkmcnt(0)\n\ts_barrier" ::: "memory"); } while (0)
; #define ATT_SB() __builtin_amdgcn_sched_barrier(0)
; #define ATT_VRD(arr, ks) do { _Pragma("unroll") for (int cb = 0; cb < NCB; ++cb) { arr[cb][0] = vtr(vbp_ + voff[cb][0] + 4096 * (ks)); arr[cb][1] = vtr(vbp_ + voff[cb][1] + 4096 * (ks)); } } while (0)
; #define ATT_MM(arr, ks) do { _Pragma("unroll") for (int cb = 0; cb < NCB; ++cb) { const bf16x8 vf = {arr[cb][0][0], arr[cb][0][1], arr[cb][0][2], arr[cb][0][3], arr[cb][1][0], arr[cb][1][1], arr[cb][1][2], arr[cb][1][3]}; o[cb] = MFMA32(vf, pf[ks], o[cb]); } } while (0)
; template <bool FOX> ...
;     ...
;         ATT_SB();
;         f32x2v ps2 = {0.f, 0.f};
;         ATT_MM(va, 0); ATT_VRD(va, 1); ATT_EXPCH(s0, 0, pf[0]); ATT_SB();
;         ATT_MM(va, 1); ATT_VRD(va, 2); ATT_EXPCH(s0, 8, pf[1]); ATT_SB();
;         ATT_MM(va, 2); ATT_VRD(va, 3); ATT_EXPCH(s1, 0, pf[2]); ATT_SB();
;         ATT_MM(va, 3); ATT_EXPCH(s1, 8, pf[3]); ATT_SB();
;         lsum += ps2.x + ps2.y;
;         if (resc) {
; #pragma unroll
;             for (int cb = 0; cb < NCB; ++cb)
; #pragma unroll
;                 for (int r = 0; r < 16; ++r) o[cb][r] *= alpha_o;
;         }
;         pbuf = buf;
;         if (FOX && act) wmore = __any(ub - mref > ckfirst) != 0;
;         bool cont = have_next;
;         if (FOX) { if (lane == 0) flags[buf * 8 + wid] = wmore ? 1 : 0; }
;         ATT_WAIT_BAR(have_next2);
.LBB0_578:
	s_waitcnt lgkmcnt(0)
	v_mfma_f32_32x32x16_bf16 v[80:95], v[18:21], v[148:151], v[80:95]
	v_exp_f32_e32 v128, v128
	v_exp_f32_e32 v129, v129
	v_exp_f32_e32 v130, v130
	ds_read_b64_tr_b16 v[18:19], v17 offset:20480
	ds_read_b64_tr_b16 v[20:21], v31 offset:20480
	v_mfma_f32_32x32x16_bf16 v[64:79], v[22:25], v[148:151], v[64:79]
	v_exp_f32_e32 v131, v131
	v_exp_f32_e32 v132, v132
	v_add_f32_e32 v254, v128, v130
	v_add_f32_e32 v255, v129, v131
	ds_read_b64_tr_b16 v[22:23], v168 offset:20480
	ds_read_b64_tr_b16 v[24:25], v169 offset:20480
	v_mfma_f32_32x32x16_bf16 v[48:63], v[26:29], v[148:151], v[48:63]
	v_exp_f32_e32 v133, v133
	v_exp_f32_e32 v134, v134
	v_add_f32_e32 v254, v254, v132
	v_add_f32_e32 v255, v255, v133
	ds_read_b64_tr_b16 v[26:27], v170 offset:20480
	ds_read_b64_tr_b16 v[28:29], v171 offset:20480
	v_mfma_f32_32x32x16_bf16 v[32:47], v[164:167], v[148:151], v[32:47]
	v_exp_f32_e32 v135, v135
	v_add_f32_e32 v254, v254, v134
	ds_read_b64_tr_b16 v[164:165], v172 offset:20480
	ds_read_b64_tr_b16 v[166:167], v173 offset:20480
	v_add_f32_e32 v255, v255, v135
	v_cvt_pk_bf16_f32 v148, v128, v129
	v_cvt_pk_bf16_f32 v149, v130, v131
	v_cvt_pk_bf16_f32 v150, v132, v133
	v_cvt_pk_bf16_f32 v151, v134, v135
	s_waitcnt lgkmcnt(0)
	v_mfma_f32_32x32x16_bf16 v[80:95], v[18:21], v[152:155], v[80:95]
	v_exp_f32_e32 v136, v136
	v_exp_f32_e32 v137, v137
	v_exp_f32_e32 v138, v138
	ds_read_b64_tr_b16 v[18:19], v17 offset:24576
	ds_read_b64_tr_b16 v[20:21], v31 offset:24576
	v_mfma_f32_32x32x16_bf16 v[64:79], v[22:25], v[152:155], v[64:79]
	v_exp_f32_e32 v139, v139
	v_exp_f32_e32 v140, v140
	v_add_f32_e32 v254, v254, v136
	v_add_f32_e32 v255, v255, v137
	ds_read_b64_tr_b16 v[22:23], v168 offset:24576
	ds_read_b64_tr_b16 v[24:25], v169 offset:24576
	v_mfma_f32_32x32x16_bf16 v[48:63], v[26:29], v[152:155], v[48:63]
	v_exp_f32_e32 v141, v141
	v_exp_f32_e32 v142, v142
	v_add_f32_e32 v254, v254, v138
	v_add_f32_e32 v255, v255, v139
	ds_read_b64_tr_b16 v[26:27], v170 offset:24576
	ds_read_b64_tr_b16 v[28:29], v171 offset:24576
	v_mfma_f32_32x32x16_bf16 v[32:47], v[164:167], v[152:155], v[32:47]
	v_exp_f32_e32 v143, v143
	v_add_f32_e32 v254, v254, v140
	v_add_f32_e32 v255, v255, v141
	ds_read_b64_tr_b16 v[164:165], v172 offset:24576
	ds_read_b64_tr_b16 v[166:167], v173 offset:24576
	v_add_f32_e32 v254, v254, v142
	v_add_f32_e32 v255, v255, v143
	v_cvt_pk_bf16_f32 v152, v136, v137
	v_cvt_pk_bf16_f32 v153, v138, v139
	v_cvt_pk_bf16_f32 v154, v140, v141
	v_cvt_pk_bf16_f32 v155, v142, v143
	s_waitcnt lgkmcnt(0)
	v_mfma_f32_32x32x16_bf16 v[80:95], v[18:21], v[160:163], v[80:95]
	v_exp_f32_e32 v112, v112
	v_exp_f32_e32 v113, v113
	v_exp_f32_e32 v114, v114
	ds_read_b64_tr_b16 v[18:19], v17 offset:28672
	ds_read_b64_tr_b16 v[20:21], v31 offset:28672
	v_mfma_f32_32x32x16_bf16 v[64:79], v[22:25], v[160:163], v[64:79]
	v_exp_f32_e32 v115, v115
	v_exp_f32_e32 v116, v116
	v_add_f32_e32 v254, v254, v112
	v_add_f32_e32 v255, v255, v113
	ds_read_b64_tr_b16 v[22:23], v168 offset:28672
	ds_read_b64_tr_b16 v[24:25], v169 offset:28672
	v_mfma_f32_32x32x16_bf16 v[48:63], v[26:29], v[160:163], v[48:63]
	v_exp_f32_e32 v117, v117
	v_exp_f32_e32 v118, v118
	v_add_f32_e32 v254, v254, v114
	v_add_f32_e32 v255, v255, v115
	ds_read_b64_tr_b16 v[26:27], v170 offset:28672
	ds_read_b64_tr_b16 v[28:29], v171 offset:28672
	v_mfma_f32_32x32x16_bf16 v[32:47], v[164:167], v[160:163], v[32:47]
	v_exp_f32_e32 v119, v119
	v_add_f32_e32 v254, v254, v116
	v_add_f32_e32 v255, v255, v117
	ds_read_b64_tr_b16 v[164:165], v172 offset:28672
	ds_read_b64_tr_b16 v[166:167], v173 offset:28672
	v_add_f32_e32 v254, v254, v118
	v_add_f32_e32 v255, v255, v119
	v_cvt_pk_bf16_f32 v160, v112, v113
	v_cvt_pk_bf16_f32 v161, v114, v115
	v_cvt_pk_bf16_f32 v162, v116, v117
	v_cvt_pk_bf16_f32 v163, v118, v119
	s_waitcnt lgkmcnt(0)
	s_and_b64 vcc, exec, s[10:11]
	s_cbranch_vccnz .Ldiff_bar0
	s_waitcnt vmcnt(4)
	s_barrier
	s_branch .Ldiff_st3

; __device__ __forceinline__ int rfl(int v) { return __builtin_amdgcn_readfirstlane(v); }
; #define ATT_WAIT_BAR(pending) do { if (pending) { if (FOX) asm volatile("s_waitcnt vmcnt(5) lgkmcnt(0)\n\ts_barrier" ::: "memory"); else asm volatile("s_waitcnt vmcnt(4) lgkmcnt(0)\n\ts_barrier" ::: "memory"); } \
;         else asm volatile("s_waitcnt vmcnt(0) lgkmcnt(0)\n\ts_barrier" ::: "memory"); } while (0)
; #define ATT_SB() __builtin_amdgcn_sched_barrier(0)
; #define ATT_MM(arr, ks) do { _Pragma("unroll") for (int cb = 0; cb < NCB; ++cb) { const bf16x8 vf = {arr[cb][0][0], arr[cb][0][1], arr[cb][0][2], arr[cb][0][3], arr[cb][1][0], arr[cb][1][1], arr[cb][1][2], arr[cb][1][3]}; o[cb] = MFMA32(vf, pf[ks], o[cb]); } } while (0)
; template <bool FOX> ...
;     ...
;         ATT_MM(va, 3); ATT_EXPCH(s1, 8, pf[3]); ATT_SB();
;         lsum += ps2.x + ps2.y;
;         if (resc) {
; #pragma unroll
;             for (int cb = 0; cb < NCB; ++cb)
; #pragma unroll
;                 for (int r = 0; r < 16; ++r) o[cb][r] *= alpha_o;
;         }
;         pbuf = buf;
;         if (FOX && act) wmore = __any(ub - mref > ckfirst) != 0;
;         bool cont = have_next;
;         if (FOX) { if (lane == 0) flags[buf * 8 + wid] = wmore ? 1 : 0; }
;         ATT_WAIT_BAR(have_next2);
;         if (FOX && cont) { int any_ = 0;
; #pragma unroll
;             for (int w8 = 0; w8 < 8; ++w8) any_ |= flags[buf * 8 + w8];
;             cont = rfl(any_) != 0; }
;         if (!cont) break;
;         t = tn; buf = nbuf;
;     }
;     u32x2 gpre[NCB][4];
; #pragma unroll
;     for (int cb = 0; cb < NCB; ++cb)
; #pragma unroll
;         for (int gq = 0; gq < 4; ++gq) gpre[cb][gq] = (u32x2){0u, 0u};
;     if (FOX || stream == 0) {
;         const bf16_t* gp_ = G + (rowb + qrow) * 512 + 128 * g + (FOX ? 64 * stream : 0) + 4 * hi;
; #pragma unroll
;         for (int cb = 0; cb < NCB; ++cb)
; #pragma unroll
;             for (int gq = 0; gq < 4; ++gq) gpre[cb][gq] = *(const u32x2*)(gp_ + 32 * cb + 8 * gq);
;     }
.Ldiff_st3:
	v_mfma_f32_32x32x16_bf16 v[80:95], v[18:21], v[156:159], v[80:95]
	v_exp_f32_e32 v120, v120
	v_exp_f32_e32 v121, v121
	v_exp_f32_e32 v122, v122
	v_mfma_f32_32x32x16_bf16 v[64:79], v[22:25], v[156:159], v[64:79]
	v_exp_f32_e32 v123, v123
	v_exp_f32_e32 v124, v124
	v_add_f32_e32 v254, v254, v120
	v_add_f32_e32 v255, v255, v121
	v_mfma_f32_32x32x16_bf16 v[48:63], v[26:29], v[156:159], v[48:63]
	v_exp_f32_e32 v125, v125
	v_exp_f32_e32 v126, v126
	v_add_f32_e32 v254, v254, v122
	v_add_f32_e32 v255, v255, v123
	v_mfma_f32_32x32x16_bf16 v[32:47], v[164:167], v[156:159], v[32:47]
	v_exp_f32_e32 v127, v127
	v_add_f32_e32 v254, v254, v124
	v_add_f32_e32 v255, v255, v125
	v_add_f32_e32 v254, v254, v126
	v_add_f32_e32 v255, v255, v127
	v_cvt_pk_bf16_f32 v156, v120, v121
	v_cvt_pk_bf16_f32 v157, v122, v123
	v_cvt_pk_bf16_f32 v158, v124, v125
	v_cvt_pk_bf16_f32 v159, v126, v127
	s_andn2_b64 vcc, exec, s[6:7]
	s_cbranch_vccz .LBB0_584
.LBB0_582:
	s_add_i32 s6, s22, 1
	v_add_f32_e32 v17, v254, v255
	s_and_b32 s6, s6, 3
	s_add_i32 s19, s19, 1
	s_add_i32 s16, s16, 64
	s_cmp_lg_u32 s18, s19
	v_add_f32_e32 v244, v244, v17
	s_cbranch_scc0 .LBB0_586
	s_mov_b32 s23, s22
	s_branch .LBB0_562
.LBB0_584:
	v_pk_mul_f32 v[94:95], v[30:31], v[94:95] op_sel_hi:[0,1]
	v_pk_mul_f32 v[92:93], v[30:31], v[92:93] op_sel_hi:[0,1]
	v_pk_mul_f32 v[90:91], v[30:31], v[90:91] op_sel_hi:[0,1]
	v_pk_mul_f32 v[88:89], v[30:31], v[88:89] op_sel_hi:[0,1]
	v_pk_mul_f32 v[86:87], v[30:31], v[86:87] op_sel_hi:[0,1]
	v_pk_mul_f32 v[84:85], v[30:31], v[84:85] op_sel_hi:[0,1]
	v_pk_mul_f32 v[82:83], v[30:31], v[82:83] op_sel_hi:[0,1]
	v_pk_mul_f32 v[80:81], v[30:31], v[80:81] op_sel_hi:[0,1]
	v_pk_mul_f32 v[78:79], v[30:31], v[78:79] op_sel_hi:[0,1]
	v_pk_mul_f32 v[76:77], v[30:31], v[76:77] op_sel_hi:[0,1]
	v_pk_mul_f32 v[74:75], v[30:31], v[74:75] op_sel_hi:[0,1]
	v_pk_mul_f32 v[72:73], v[30:31], v[72:73] op_sel_hi:[0,1]
	v_pk_mul_f32 v[70:71], v[30:31], v[70:71] op_sel_hi:[0,1]
	v_pk_mul_f32 v[68:69], v[30:31], v[68:69] op_sel_hi:[0,1]
	v_pk_mul_f32 v[66:67], v[30:31], v[66:67] op_sel_hi:[0,1]
	v_pk_mul_f32 v[64:65], v[30:31], v[64:65] op_sel_hi:[0,1]
	v_pk_mul_f32 v[62:63], v[30:31], v[62:63] op_sel_hi:[0,1]
	v_pk_mul_f32 v[60:61], v[30:31], v[60:61] op_sel_hi:[0,1]
	v_pk_mul_f32 v[58:59], v[30:31], v[58:59] op_sel_hi:[0,1]
	v_pk_mul_f32 v[56:57], v[30:31], v[56:57] op_sel_hi:[0,1]
	v_pk_mul_f32 v[54:55], v[30:31], v[54:55] op_sel_hi:[0,1]
	v_pk_mul_f32 v[52:53], v[30:31], v[52:53] op_sel_hi:[0,1]
	v_pk_mul_f32 v[50:51], v[30:31], v[50:51] op_sel_hi:[0,1]
	v_pk_mul_f32 v[48:49], v[30:31], v[48:49] op_sel_hi:[0,1]
	v_pk_mul_f32 v[46:47], v[30:31], v[46:47] op_sel_hi:[0,1]
	v_pk_mul_f32 v[44:45], v[30:31], v[44:45] op_sel_hi:[0,1]
	v_pk_mul_f32 v[42:43], v[30:31], v[42:43] op_sel_hi:[0,1]
	v_pk_mul_f32 v[40:41], v[30:31], v[40:41] op_sel_hi:[0,1]
	v_pk_mul_f32 v[38:39], v[30:31], v[38:39] op_sel_hi:[0,1]
	v_pk_mul_f32 v[36:37], v[30:31], v[36:37] op_sel_hi:[0,1]
	v_pk_mul_f32 v[34:35], v[30:31], v[34:35] op_sel_hi:[0,1]
	v_pk_mul_f32 v[32:33], v[30:31], v[32:33] op_sel_hi:[0,1]
	s_branch .LBB0_582
.LBB0_586:
	s_setprio 0
	s_lshl_b32 s0, s34, 7
	s_cmp_lt_u32 s21, 4
	s_cselect_b64 s[4:5], -1, 0
	s_cmp_gt_u32 s21, 3
	v_lshlrev_b32_e32 v2, 3, v1
	s_cbranch_scc1 .LBB0_588
	v_readlane_b32 s6, v253, 12
	v_lshlrev_b64 v[4:5], 10, v[194:195]
	v_readlane_b32 s7, v253, 13
	s_lshl_b32 s16, s0, 1
	v_mov_b32_e32 v3, v0
	v_lshl_add_u64 v[4:5], s[6:7], 0, v[4:5]
	v_lshl_add_u64 v[4:5], v[4:5], 0, s[16:17]
	v_lshl_add_u64 v[6:7], v[4:5], 0, v[2:3]
	global_load_dwordx2 v[4:5], v[6:7], off
	global_load_dwordx2 v[12:13], v[6:7], off offset:16
	global_load_dwordx2 v[10:11], v[6:7], off offset:32
	global_load_dwordx2 v[24:25], v[6:7], off offset:48
	global_load_dwordx2 v[22:23], v[6:7], off offset:64
	global_load_dwordx2 v[114:115], v[6:7], off offset:80
	global_load_dwordx2 v[112:113], v[6:7], off offset:96
	global_load_dwordx2 v[110:111], v[6:7], off offset:112
	global_load_dwordx2 v[108:109], v[6:7], off offset:128
	global_load_dwordx2 v[106:107], v[6:7], off offset:144
	global_load_dwordx2 v[104:105], v[6:7], off offset:160
	global_load_dwordx2 v[102:103], v[6:7], off offset:176
	global_load_dwordx2 v[30:31], v[6:7], off offset:192
	global_load_dwordx2 v[100:101], v[6:7], off offset:208
	global_load_dwordx2 v[98:99], v[6:7], off offset:224
	global_load_dwordx2 v[96:97], v[6:7], off offset:240
	s_branch .LBB0_589

; __global__ void __launch_bounds__(512, 2) hymba_fwd(Args a) {
	.amdhsa_kernel _Z9hymba_fwd4Args
		.amdhsa_group_segment_fixed_size 0
		.amdhsa_private_segment_fixed_size 0
		.amdhsa_kernarg_size 416
		.amdhsa_user_sgpr_count 2
		.amdhsa_user_sgpr_dispatch_ptr 0
		.amdhsa_user_sgpr_queue_ptr 0
		.amdhsa_user_sgpr_kernarg_segment_ptr 1
		.amdhsa_user_sgpr_dispatch_id 0
		.amdhsa_user_sgpr_kernarg_preload_length 0
		.amdhsa_user_sgpr_kernarg_preload_offset 0
		.amdhsa_user_sgpr_private_segment_size 0
		.amdhsa_uses_dynamic_stack 0
		.amdhsa_enable_private_segment 0
		.amdhsa_system_sgpr_workgroup_id_x 1
		.amdhsa_system_sgpr_workgroup_id_y 0
		.amdhsa_system_sgpr_workgroup_id_z 0
		.amdhsa_system_sgpr_workgroup_info 0
		.amdhsa_system_vgpr_workitem_id 2
		.amdhsa_next_free_vgpr 256
		.amdhsa_next_free_sgpr 100
		.amdhsa_accum_offset 256
		.amdhsa_reserve_vcc 1
		.amdhsa_float_round_mode_32 0
		.amdhsa_float_round_mode_16_64 0
		.amdhsa_float_denorm_mode_32 3
		.amdhsa_float_denorm_mode_16_64 3
		.amdhsa_dx10_clamp 1
		.amdhsa_ieee_mode 1
		.amdhsa_fp16_overflow 0
		.amdhsa_tg_split 0
		.amdhsa_exception_fp_ieee_invalid_op 0
		.amdhsa_exception_fp_denorm_src 0
		.amdhsa_exception_fp_ieee_div_zero 0
		.amdhsa_exception_fp_ieee_overflow 0
		.amdhsa_exception_fp_ieee_underflow 0
		.amdhsa_exception_fp_ieee_inexact 0
		.amdhsa_exception_int_div_zero 0
	.end_amdhsa_kernel

; __global__ void __launch_bounds__(512, 2) hymba_fwd(Args a) {
amdhsa.kernels:
  - .agpr_count:     0
    .args:
      - .offset:         0
        .size:           160
        .value_kind:     by_value
      - .offset:         160
        .size:           4
        .value_kind:     hidden_block_count_x
      - .offset:         164
        .size:           4
        .value_kind:     hidden_block_count_y
      - .offset:         168
        .size:           4
        .value_kind:     hidden_block_count_z
      - .offset:         172
        .size:           2
        .value_kind:     hidden_group_size_x
      - .offset:         174
        .size:           2
        .value_kind:     hidden_group_size_y
      - .offset:         176
        .size:           2
        .value_kind:     hidden_group_size_z
      - .offset:         178
        .size:           2
        .value_kind:     hidden_remainder_x
      - .offset:         180
        .size:           2
        .value_kind:     hidden_remainder_y
      - .offset:         182
        .size:           2
        .value_kind:     hidden_remainder_z
      - .offset:         200
        .size:           8
        .value_kind:     hidden_global_offset_x
      - .offset:         208
        .size:           8
        .value_kind:     hidden_global_offset_y
      - .offset:         216
        .size:           8
        .value_kind:     hidden_global_offset_z
      - .offset:         224
        .size:           2
        .value_kind:     hidden_grid_dims
      - .offset:         248
        .size:           8
        .value_kind:     hidden_multigrid_sync_arg
      - .offset:         280
        .size:           4
        .value_kind:     hidden_dynamic_lds_size
    .group_segment_fixed_size: 0
    .kernarg_segment_align: 8
    .kernarg_segment_size: 416
    .language:       OpenCL C
    .language_version:
      - 2
      - 0
    .max_flat_workgroup_size: 512
    .name:           _Z9hymba_fwd4Args
    .private_segment_fixed_size: 0
    .sgpr_count:     106
    .sgpr_spill_count: 220
    .symbol:         _Z9hymba_fwd4Args.kd
    .uniform_work_group_size: 1
    .uses_dynamic_stack: false
    .vgpr_count:     256
    .vgpr_spill_count: 0
    .wavefront_size: 64
